# GEMM1 epilogue: the 64 acc+0 packed adds per wave dropped, conversions read the accumulators directly into rotating fresh quads; on top of g1zero
# baseline (speedup 1.0000x reference)
.LBB0_292:
	v_lshl_or_b32 v140, s78, 8, v143
	v_ashrrev_i32_e32 v141, 31, v140
	v_lshl_add_u32 v145, s79, 8, v129
	v_lshl_add_u64 v[140:141], v[140:141], 1, s[36:37]
	v_cvt_pk_bf16_f32 v156, v124, v125
	v_cvt_pk_bf16_f32 v157, v126, v127
	v_mad_i64_i32 v[146:147], s[58:59], v145, s3, v[140:141]
	v_cvt_pk_bf16_f32 v158, v120, v121
	v_cvt_pk_bf16_f32 v159, v122, v123
	global_store_dwordx4 v[146:147], v[156:159], off sc1
	s_nop 1
	v_cvt_pk_bf16_f32 v160, v116, v117
	v_cvt_pk_bf16_f32 v161, v118, v119
	v_cvt_pk_bf16_f32 v162, v108, v109
	v_cvt_pk_bf16_f32 v163, v110, v111
	v_lshl_add_u64 v[116:117], v[146:147], 0, s[10:11]
	global_store_dwordx4 v[116:117], v[160:163], off sc1
	s_nop 1
	v_or_b32_e32 v108, 16, v145
	v_cvt_pk_bf16_f32 v164, v112, v113
	v_cvt_pk_bf16_f32 v165, v114, v115
	v_mad_i64_i32 v[108:109], s[58:59], v108, s3, v[140:141]
	v_cvt_pk_bf16_f32 v166, v104, v105
	v_cvt_pk_bf16_f32 v167, v106, v107
	global_store_dwordx4 v[108:109], v[164:167], off sc1
	s_nop 1
	v_cvt_pk_bf16_f32 v168, v100, v101
	v_cvt_pk_bf16_f32 v169, v102, v103
	v_cvt_pk_bf16_f32 v170, v92, v93
	v_cvt_pk_bf16_f32 v171, v94, v95
	v_lshl_add_u64 v[100:101], v[108:109], 0, s[10:11]
	global_store_dwordx4 v[100:101], v[168:171], off sc1
	s_nop 1
	v_or_b32_e32 v92, 32, v145
	v_cvt_pk_bf16_f32 v172, v96, v97
	v_cvt_pk_bf16_f32 v173, v98, v99
	v_mad_i64_i32 v[92:93], s[58:59], v92, s3, v[140:141]
	v_cvt_pk_bf16_f32 v174, v88, v89
	v_cvt_pk_bf16_f32 v175, v90, v91
	global_store_dwordx4 v[92:93], v[172:175], off sc1
	s_nop 1
	v_cvt_pk_bf16_f32 v176, v84, v85
	v_cvt_pk_bf16_f32 v177, v86, v87
	v_cvt_pk_bf16_f32 v178, v76, v77
	v_cvt_pk_bf16_f32 v179, v78, v79
	v_lshl_add_u64 v[84:85], v[92:93], 0, s[10:11]
	global_store_dwordx4 v[84:85], v[176:179], off sc1
	s_nop 1
	v_or_b32_e32 v76, 48, v145
	v_cvt_pk_bf16_f32 v180, v80, v81
	v_cvt_pk_bf16_f32 v181, v82, v83
	v_mad_i64_i32 v[76:77], s[58:59], v76, s3, v[140:141]
	v_cvt_pk_bf16_f32 v182, v72, v73
	v_cvt_pk_bf16_f32 v183, v74, v75
	global_store_dwordx4 v[76:77], v[180:183], off sc1
	s_nop 1
	v_cvt_pk_bf16_f32 v184, v68, v69
	v_cvt_pk_bf16_f32 v185, v70, v71
	v_cvt_pk_bf16_f32 v186, v64, v65
	v_cvt_pk_bf16_f32 v187, v66, v67
	v_lshl_add_u64 v[68:69], v[76:77], 0, s[10:11]
	global_store_dwordx4 v[68:69], v[184:187], off sc1
	s_nop 1
	v_add_u32_e32 v64, 0x80, v145
	v_cvt_pk_bf16_f32 v156, v60, v61
	v_cvt_pk_bf16_f32 v157, v62, v63
	v_mad_i64_i32 v[64:65], s[58:59], v64, s3, v[140:141]
	v_cvt_pk_bf16_f32 v158, v56, v57
	v_cvt_pk_bf16_f32 v159, v58, v59
	global_store_dwordx4 v[64:65], v[156:159], off sc1
	s_nop 1
	v_cvt_pk_bf16_f32 v160, v52, v53
	v_cvt_pk_bf16_f32 v161, v54, v55
	v_cvt_pk_bf16_f32 v162, v44, v45
	v_cvt_pk_bf16_f32 v163, v46, v47
	v_lshl_add_u64 v[52:53], v[64:65], 0, s[10:11]
	global_store_dwordx4 v[52:53], v[160:163], off sc1
	s_nop 1
	v_add_u32_e32 v44, 0x90, v145
	v_cvt_pk_bf16_f32 v164, v48, v49
	v_cvt_pk_bf16_f32 v165, v50, v51
	v_mad_i64_i32 v[44:45], s[58:59], v44, s3, v[140:141]
	v_cvt_pk_bf16_f32 v166, v40, v41
	v_cvt_pk_bf16_f32 v167, v42, v43
	global_store_dwordx4 v[44:45], v[164:167], off sc1
	s_nop 1
	v_cvt_pk_bf16_f32 v168, v36, v37
	v_cvt_pk_bf16_f32 v169, v38, v39
	v_cvt_pk_bf16_f32 v170, v28, v29
	v_cvt_pk_bf16_f32 v171, v30, v31
	v_lshl_add_u64 v[36:37], v[44:45], 0, s[10:11]
	global_store_dwordx4 v[36:37], v[168:171], off sc1
	s_nop 1
	v_add_u32_e32 v28, 0xa0, v145
	v_cvt_pk_bf16_f32 v172, v32, v33
	v_cvt_pk_bf16_f32 v173, v34, v35
	v_mad_i64_i32 v[28:29], s[58:59], v28, s3, v[140:141]
	v_cvt_pk_bf16_f32 v174, v24, v25
	v_cvt_pk_bf16_f32 v175, v26, v27
	global_store_dwordx4 v[28:29], v[172:175], off sc1
	s_nop 1
	v_cvt_pk_bf16_f32 v176, v20, v21
	v_cvt_pk_bf16_f32 v177, v22, v23
	v_cvt_pk_bf16_f32 v178, v12, v13
	v_cvt_pk_bf16_f32 v179, v14, v15
	v_lshl_add_u64 v[20:21], v[28:29], 0, s[10:11]
	global_store_dwordx4 v[20:21], v[176:179], off sc1
	s_nop 1
	v_add_u32_e32 v12, 0xb0, v145
	v_cvt_pk_bf16_f32 v180, v16, v17
	v_cvt_pk_bf16_f32 v181, v18, v19
	v_mad_i64_i32 v[12:13], s[58:59], v12, s3, v[140:141]
	v_cvt_pk_bf16_f32 v182, v8, v9
	v_cvt_pk_bf16_f32 v183, v10, v11
	global_store_dwordx4 v[12:13], v[180:183], off sc1
	s_nop 1
	v_cvt_pk_bf16_f32 v184, v4, v5
	v_lshl_add_u64 v[4:5], v[12:13], 0, s[10:11]
	v_cvt_pk_bf16_f32 v185, v6, v7
	v_cvt_pk_bf16_f32 v186, v0, v1
	v_cvt_pk_bf16_f32 v187, v2, v3
	s_andn2_b64 vcc, exec, s[40:41]
	global_store_dwordx4 v[4:5], v[184:187], off sc1
	s_nop 1
	s_mov_b64 s[40:41], -1
	s_cbranch_vccnz .LBB0_285
	s_andn2_b64 vcc, exec, s[34:35]
	s_cbranch_vccnz .LBB0_284
	s_barrier
	s_branch .LBB0_284
